# SB and FoX items: output-gate loads issued at item start
# baseline (speedup 1.0000x reference)
; __device__ __forceinline__ float bflo(unsigned u) { return __uint_as_float(u << 16); }
; __device__ __forceinline__ float bfhi(unsigned u) { return __uint_as_float(u & 0xffff0000u); }
; template <int MODE>
; __device__ __forceinline__ void attn_item(const AttnP& p, int b, int h, int qb, LAS unsigned char* lds) {
;     ...
;     const int tok0 = b * SEQ, q0 = qb * 256, qw = q0 + 32 * w, qrow = qw + ln;
;     const bf16_t* P = p.P;
;     bf16x8 Qf[NC][4];
; #pragma unroll
;     for (int c = 0; c < NC; ++c) {
;         u32x4 raw[4]; float ss = 0.f;
; #pragma unroll
;         for (int ks = 0; ks < 4; ++ks) {
;             raw[ks] = *(const u32x4*)(P + (size_t)(tok0 + qrow) * PP + qcol + c * 64 + ks * 16 + hh * 8);
; #pragma unroll
;             for (int e = 0; e < 4; ++e) { const float lo = bflo(raw[ks][e]), hi = bfhi(raw[ks][e]); ss += lo * lo + hi * hi; }
;         }
;     ...
;     const float fb = (MODE == 2) ? p.fbias[h] : 0.f;
;     const int jt_max = qb * 4 + 3;
;     u32x4 kreg[NC], vreg[NC]; float cfreg = 0.f;
.LBB0_213:
	s_or_b64 exec, exec, s[0:1]
	v_readlane_b32 s0, v254, 19
	s_waitcnt lgkmcnt(0)
	s_barrier
	v_mov_b32_e32 v0, s0
	ds_read_b32 v0, v0
	s_movk_i32 s0, 0x4ff
	s_waitcnt lgkmcnt(0)
	v_cmp_lt_i32_e32 vcc, s0, v0
	v_readfirstlane_b32 s3, v0
	s_mov_b64 s[0:1], -1
	s_cbranch_vccnz .LBB0_210
	s_cmpk_gt_i32 s3, 0xff
	v_writelane_b32 v252, s3, 9
	s_cbranch_scc0 .LBB0_243
	s_add_i32 s0, s3, 0xffffff00
	v_mov_b32_e32 v123, v210
	s_lshr_b32 s22, s0, 6
	s_sub_i32 s2, 15, s22
	v_readfirstlane_b32 s5, v123
	s_lshl_b32 s0, s3, 9
	s_ashr_i32 s1, s5, 1
	s_and_b32 s26, s0, 0x7000
	s_lshl_b32 s0, s2, 8
	s_and_b32 s27, s1, 0xffffffe0
	v_and_b32_e32 v122, 31, v123
	s_add_i32 s27, s27, s0
	v_or_b32_e32 v115, s27, v122
	s_and_b32 s4, s3, 7
	v_add_u32_e32 v0, s26, v115
	s_waitcnt vmcnt(0)
	v_mov_b64_e32 v[2:3], s[68:69]
	v_bfe_u32 v124, v123, 5, 1
	v_mad_i64_i32 v[2:3], s[0:1], v0, s76, v[2:3]
	s_lshl_b32 s92, s4, 7
	v_lshl_add_u64 v[2:3], v[2:3], 0, s[92:93]
	v_lshlrev_b32_e32 v248, 3, v124
	v_mov_b32_e32 v249, 0
	v_lshl_add_u64 v[248:249], v[2:3], 0, v[248:249]
	global_load_dwordx2 v[194:195], v[248:249], off offset:3072
	global_load_dwordx2 v[196:197], v[248:249], off offset:3088
	global_load_dwordx2 v[198:199], v[248:249], off offset:3104
	global_load_dwordx2 v[200:201], v[248:249], off offset:3120
	global_load_dwordx2 v[202:203], v[248:249], off offset:3136
	global_load_dwordx2 v[204:205], v[248:249], off offset:3152
	global_load_dwordx2 v[250:251], v[248:249], off offset:3168
	global_load_dwordx2 v[248:249], v[248:249], off offset:3184
	v_lshlrev_b32_e32 v88, 4, v124
	v_mov_b32_e32 v89, v1
	v_lshl_add_u64 v[2:3], v[2:3], 0, v[88:89]
	global_load_dwordx4 v[64:67], v[2:3], off offset:96
	global_load_dwordx4 v[68:71], v[2:3], off offset:64
	global_load_dwordx4 v[100:103], v[2:3], off offset:32
	global_load_dwordx4 v[116:119], v[2:3], off
	s_lshl_b32 s100, s2, 2
	s_or_b32 s100, s100, 3
	s_lshl_b32 s100, s100, 6
	s_or_b32 s100, s100, s26
	v_ashrrev_i32_e32 v156, 3, v123
	v_add_u32_e32 v156, s100, v156
	v_mov_b64_e32 v[154:155], s[68:69]
	v_mad_i64_i32 v[154:155], vcc, v156, s76, v[154:155]
	v_lshlrev_b32_e32 v156, 3, v123
	v_and_b32_e32 v156, 56, v156
	v_lshlrev_b32_e32 v156, 1, v156
	v_mov_b32_e32 v157, 0
	v_lshl_add_u64 v[154:155], v[154:155], 0, v[156:157]
	v_lshl_add_u64 v[154:155], v[154:155], 0, s[92:93]
	global_load_dwordx4 v[142:145], v[154:155], off offset:1024
	global_load_dwordx4 v[146:149], v[154:155], off offset:2048
	v_mov_b32_e32 v150, 0
	s_cmp_gt_u32 s5, 63
	s_cbranch_scc1 .Lfp_nocf
	v_and_b32_e32 v156, 63, v123
	v_or_b32_e32 v156, s100, v156
	v_mul_u32_u24_e32 v156, 0x50, v156
	v_or_b32_e32 v156, s4, v156
	v_lshl_add_u32 v156, v156, 2, v217
	global_load_dword v150, v156, s[84:85]

; __device__ __forceinline__ float bflo(unsigned u) { return __uint_as_float(u << 16); }
; __device__ __forceinline__ float bfhi(unsigned u) { return __uint_as_float(u & 0xffff0000u); }
; __device__ __forceinline__ float silu(float g) { return g * __builtin_amdgcn_rcpf(1.0f + __expf(-g)); }
; template <int MODE>
; __device__ __forceinline__ void attn_item(const AttnP& p, int b, int h, int qb, LAS unsigned char* lds) {
;     ...
;     if (MODE != 1) { float l0 = lsum[0]; l0 += __shfl_xor(l0, 32); inv0 = 1.0f / l0; }
;     if (MODE == 0) { float l1 = lsum[NC - 1]; l1 += __shfl_xor(l1, 32); inv1 = p.lam / l1; }
;     float ss = 0.f;
; #pragma unroll
;     for (int d = 0; d < DV / 32; ++d)
; #pragma unroll
;         for (int i = 0; i < 16; ++i) {
;             float o = O[0][d][i] * inv0;
;             if (MODE == 0) o -= O[NC - 1][d][i] * inv1;
;             O[0][d][i] = o; ss += o * o;
;         }
;     ss += __shfl_xor(ss, 32);
;     float rn = 1.0f / sqrtf(ss * (1.0f / DV) + 1e-6f);
;     if (MODE == 0) rn *= p.oml;
;     int qrow_e = qrow; asm volatile("" : "+v"(qrow_e));
;     const size_t trow = (size_t)(tok0 + qrow_e);
; #pragma unroll
;     for (int d = 0; d < DV / 32; ++d)
; #pragma unroll
;         for (int g = 0; g < 4; ++g) {
;             const int dd = d * 32 + 8 * g + 4 * hh;
;             const u32x2 gr = *(const u32x2*)(P + trow * PP + gcol + dd);
;             const f32x4 og = *(const f32x4*)(p.out_gain + gaincol + dd);
;             const float o0 = O[0][d][4 * g] * rn * og[0] * silu(bflo(gr.x)), o1 = O[0][d][4 * g + 1] * rn * og[1] * silu(bfhi(gr.x));
;             const float o2 = O[0][d][4 * g + 2] * rn * og[2] * silu(bflo(gr.y)), o3 = O[0][d][4 * g + 3] * rn * og[3] * silu(bfhi(gr.y));
.Lnx_af:
	ds_bpermute_b32 v2, v114, v0
	s_lshl_b32 s2, s20, 2
	s_bitset1_b32 s2, 12
	s_waitcnt lgkmcnt(0)
	v_add_f32_e32 v0, v0, v2
	v_div_scale_f32 v2, s[0:1], v0, v0, 1.0
	v_rcp_f32_e32 v3, v2
	s_nop 0
	v_fma_f32 v4, -v2, v3, 1.0
	v_fmac_f32_e32 v3, v4, v3
	v_div_scale_f32 v4, vcc, 1.0, v0, 1.0
	v_mul_f32_e32 v5, v4, v3
	v_fma_f32 v6, -v2, v5, v4
	v_fmac_f32_e32 v5, v6, v3
	v_fma_f32 v2, -v2, v5, v4
	v_div_fmas_f32 v2, v2, v3, v5
	v_div_fixup_f32 v56, v2, v0, 1.0
	v_add_u32_e32 v2, s26, v115
	v_mov_b64_e32 v[4:5], s[68:69]
	v_mad_i64_i32 v[4:5], s[0:1], v2, s76, v[4:5]
	v_lshl_add_u64 v[4:5], v[4:5], 0, s[92:93]
	v_lshlrev_b32_e32 v0, 1, v94
	v_lshl_add_u64 v[12:13], v[4:5], 0, v[0:1]
	v_mov_b64_e32 v[50:51], v[194:195]
	v_mov_b64_e32 v[54:55], v[196:197]
	s_waitcnt vmcnt(0)
	v_mov_b64_e32 v[66:67], v[198:199]
	v_mov_b64_e32 v[74:75], v[200:201]
	v_readlane_b32 s0, v254, 54
	v_readlane_b32 s1, v254, 55
	s_add_u32 s2, s0, s2
	v_ashrrev_i32_e32 v3, 31, v2
	s_addc_u32 s3, s1, 0
	v_readlane_b32 s0, v254, 40
	v_lshlrev_b64 v[10:11], 11, v[2:3]
	v_readlane_b32 s1, v254, 41
	v_mov_b64_e32 v[76:77], v[202:203]
	v_mov_b64_e32 v[86:87], v[204:205]
	v_lshl_add_u64 v[10:11], s[0:1], 0, v[10:11]
	v_lshl_add_u64 v[10:11], v[10:11], 0, s[92:93]
	v_lshl_add_u64 v[10:11], v[10:11], 0, v[0:1]
	v_pk_mul_f32 v[14:15], v[26:27], v[56:57] op_sel_hi:[1,0]
	v_pk_mul_f32 v[8:9], v[28:29], v[56:57] op_sel_hi:[1,0]
	v_pk_mul_f32 v[6:7], v[30:31], v[56:57] op_sel_hi:[1,0]
	v_lshlrev_b32_e32 v57, 2, v94
	global_load_dwordx4 v[2:5], v57, s[2:3]
	v_pk_mul_f32 v[32:33], v[32:33], v[56:57] op_sel_hi:[1,0]
	v_pk_mul_f32 v[34:35], v[34:35], v[56:57] op_sel_hi:[1,0]
	v_pk_mul_f32 v[64:65], v[32:33], v[32:33]
	v_pk_mul_f32 v[62:63], v[34:35], v[34:35]
	v_pk_mul_f32 v[36:37], v[36:37], v[56:57] op_sel_hi:[1,0]
	v_pk_mul_f32 v[38:39], v[38:39], v[56:57] op_sel_hi:[1,0]
	v_pk_mul_f32 v[72:73], v[36:37], v[36:37]
	v_pk_mul_f32 v[70:71], v[38:39], v[38:39]
	v_pk_mul_f32 v[42:43], v[42:43], v[56:57] op_sel_hi:[1,0]
	v_pk_mul_f32 v[46:47], v[46:47], v[56:57] op_sel_hi:[1,0]
	v_pk_mul_f32 v[78:79], v[42:43], v[42:43]
	v_pk_mul_f32 v[88:89], v[46:47], v[46:47]
	v_pk_mul_f32 v[16:17], v[16:17], v[56:57] op_sel_hi:[1,0]
	v_pk_mul_f32 v[18:19], v[18:19], v[56:57] op_sel_hi:[1,0]
	v_pk_mul_f32 v[94:95], v[16:17], v[16:17]
	v_pk_mul_f32 v[92:93], v[18:19], v[18:19]
	v_pk_mul_f32 v[22:23], v[22:23], v[56:57] op_sel_hi:[1,0]
	v_pk_mul_f32 v[24:25], v[24:25], v[56:57] op_sel_hi:[1,0]
	v_pk_mul_f32 v[96:97], v[22:23], v[22:23]
	v_pk_mul_f32 v[100:101], v[24:25], v[24:25]
	v_pk_mul_f32 v[26:27], v[14:15], v[14:15]
	v_pk_mul_f32 v[28:29], v[8:9], v[8:9]
	v_pk_mul_f32 v[30:31], v[6:7], v[6:7]
	s_waitcnt lgkmcnt(0)
	v_lshlrev_b32_e32 v48, 16, v50
	v_and_b32_e32 v49, 0xffff0000, v50
	v_mul_f32_e32 v50, 0xbfb8aa3b, v48
	v_exp_f32_e32 v50, v50
	s_nop 0
	v_add_f32_e32 v50, 1.0, v50
	v_rcp_f32_e32 v52, v50
	v_mul_f32_e32 v50, 0xbfb8aa3b, v49
	v_exp_f32_e32 v50, v50
	s_nop 0
	v_add_f32_e32 v50, 1.0, v50
	v_rcp_f32_e32 v53, v50
	v_lshlrev_b32_e32 v50, 16, v51
	v_and_b32_e32 v51, 0xffff0000, v51
	v_pk_mul_f32 v[48:49], v[52:53], v[48:49]
	v_mul_f32_e32 v52, 0xbfb8aa3b, v50
	v_mul_f32_e32 v53, 0xbfb8aa3b, v51
	v_exp_f32_e32 v52, v52
	v_exp_f32_e32 v53, v53
	v_add_f32_e32 v52, 1.0, v52
	v_add_f32_e32 v53, 1.0, v53
	v_rcp_f32_e32 v52, v52
	v_rcp_f32_e32 v53, v53
	s_nop 0
	v_pk_mul_f32 v[50:51], v[52:53], v[50:51]
	v_lshlrev_b32_e32 v52, 16, v54
	v_mul_f32_e32 v0, 0xbfb8aa3b, v52
	v_exp_f32_e32 v0, v0
	v_and_b32_e32 v53, 0xffff0000, v54
	v_lshlrev_b32_e32 v54, 16, v55
	v_and_b32_e32 v55, 0xffff0000, v55
	v_add_f32_e32 v0, 1.0, v0
	v_rcp_f32_e32 v58, v0
	v_mul_f32_e32 v0, 0xbfb8aa3b, v53
	v_exp_f32_e32 v0, v0
	s_nop 0
	v_add_f32_e32 v0, 1.0, v0
	v_rcp_f32_e32 v59, v0
	v_mul_f32_e32 v0, 0xbfb8aa3b, v54
	v_exp_f32_e32 v0, v0
	v_pk_mul_f32 v[52:53], v[58:59], v[52:53]
	v_add_f32_e32 v0, 1.0, v0
	v_rcp_f32_e32 v58, v0
	v_mul_f32_e32 v0, 0xbfb8aa3b, v55
	v_exp_f32_e32 v0, v0
	s_nop 0
	v_add_f32_e32 v0, 1.0, v0
	v_rcp_f32_e32 v59, v0
	s_nop 0
	v_pk_mul_f32 v[54:55], v[58:59], v[54:55]
	v_pk_mul_f32 v[58:59], v[40:41], v[56:57] op_sel_hi:[1,0]
	s_waitcnt vmcnt(0)
	v_lshlrev_b32_e32 v40, 16, v66
	v_mul_f32_e32 v0, 0xbfb8aa3b, v40
	v_exp_f32_e32 v0, v0
	v_and_b32_e32 v41, 0xffff0000, v66
	v_pk_mul_f32 v[80:81], v[58:59], v[58:59]
	v_add_f32_e32 v0, 1.0, v0
	v_rcp_f32_e32 v60, v0
	v_mul_f32_e32 v0, 0xbfb8aa3b, v41
	v_exp_f32_e32 v0, v0
	s_nop 0
	v_add_f32_e32 v0, 1.0, v0
	v_rcp_f32_e32 v61, v0
	s_nop 0
	v_pk_mul_f32 v[60:61], v[60:61], v[40:41]
	v_lshlrev_b32_e32 v40, 16, v67
	v_mul_f32_e32 v0, 0xbfb8aa3b, v40
	v_exp_f32_e32 v0, v0
	v_and_b32_e32 v41, 0xffff0000, v67
	v_add_f32_e32 v0, 1.0, v0
	v_rcp_f32_e32 v66, v0
	v_mul_f32_e32 v0, 0xbfb8aa3b, v41
	v_exp_f32_e32 v0, v0
	s_nop 0
	v_add_f32_e32 v0, 1.0, v0
	v_rcp_f32_e32 v67, v0
	s_nop 0
	v_pk_mul_f32 v[40:41], v[66:67], v[40:41]
	v_pk_mul_f32 v[66:67], v[44:45], v[56:57] op_sel_hi:[1,0]
	v_lshlrev_b32_e32 v44, 16, v74
	v_mul_f32_e32 v0, 0xbfb8aa3b, v44
	v_exp_f32_e32 v0, v0
	v_and_b32_e32 v45, 0xffff0000, v74
	v_pk_mul_f32 v[90:91], v[66:67], v[66:67]
	v_add_f32_e32 v0, 1.0, v0
	v_rcp_f32_e32 v68, v0
	v_mul_f32_e32 v0, 0xbfb8aa3b, v45
	v_exp_f32_e32 v0, v0
	s_nop 0
	v_add_f32_e32 v0, 1.0, v0
	v_rcp_f32_e32 v69, v0
	s_nop 0
	v_pk_mul_f32 v[68:69], v[68:69], v[44:45]
	v_lshlrev_b32_e32 v44, 16, v75
	v_mul_f32_e32 v0, 0xbfb8aa3b, v44
	v_exp_f32_e32 v0, v0
	v_and_b32_e32 v45, 0xffff0000, v75
	v_add_f32_e32 v0, 1.0, v0
	v_rcp_f32_e32 v74, v0
	v_mul_f32_e32 v0, 0xbfb8aa3b, v45
	v_exp_f32_e32 v0, v0
	s_nop 0
	v_add_f32_e32 v0, 1.0, v0
	v_rcp_f32_e32 v75, v0
	s_nop 0
; __device__ __forceinline__ unsigned pk2(float lo, float hi) { f32x2 v = {lo, hi}; bf16x2_t b = __builtin_convertvector(v, bf16x2_t); return __builtin_bit_cast(unsigned, b); }
; __device__ __forceinline__ float bflo(unsigned u) { return __uint_as_float(u << 16); }
; __device__ __forceinline__ float bfhi(unsigned u) { return __uint_as_float(u & 0xffff0000u); }
; __device__ __forceinline__ float silu(float g) { return g * __builtin_amdgcn_rcpf(1.0f + __expf(-g)); }
; template <int MODE>
; __device__ __forceinline__ void attn_item(const AttnP& p, int b, int h, int qb, LAS unsigned char* lds) {
;     ...
;             O[0][d][i] = o; ss += o * o;
;         }
;     ss += __shfl_xor(ss, 32);
;     float rn = 1.0f / sqrtf(ss * (1.0f / DV) + 1e-6f);
;     if (MODE == 0) rn *= p.oml;
;     int qrow_e = qrow; asm volatile("" : "+v"(qrow_e));
;     const size_t trow = (size_t)(tok0 + qrow_e);
; #pragma unroll
;     for (int d = 0; d < DV / 32; ++d)
; #pragma unroll
;         for (int g = 0; g < 4; ++g) {
;             const int dd = d * 32 + 8 * g + 4 * hh;
;             const u32x2 gr = *(const u32x2*)(P + trow * PP + gcol + dd);
;             const f32x4 og = *(const f32x4*)(p.out_gain + gaincol + dd);
;             const float o0 = O[0][d][4 * g] * rn * og[0] * silu(bflo(gr.x)), o1 = O[0][d][4 * g + 1] * rn * og[1] * silu(bfhi(gr.x));
;             const float o2 = O[0][d][4 * g + 2] * rn * og[2] * silu(bflo(gr.y)), o3 = O[0][d][4 * g + 3] * rn * og[3] * silu(bfhi(gr.y));
;             u32x2 wv; wv.x = pk2(o0, o1); wv.y = pk2(o2, o3);
;             *(u32x2*)(p.mixed + trow * 1024 + mixcol + dd) = wv;
	v_pk_mul_f32 v[44:45], v[74:75], v[44:45]
	v_lshlrev_b32_e32 v74, 16, v76
	v_mul_f32_e32 v0, 0xbfb8aa3b, v74
	v_exp_f32_e32 v0, v0
	v_and_b32_e32 v75, 0xffff0000, v76
	v_lshlrev_b32_e32 v76, 16, v77
	v_and_b32_e32 v77, 0xffff0000, v77
	v_add_f32_e32 v0, 1.0, v0
	v_rcp_f32_e32 v82, v0
	v_mul_f32_e32 v0, 0xbfb8aa3b, v75
	v_exp_f32_e32 v0, v0
	s_nop 0
	v_add_f32_e32 v0, 1.0, v0
	v_rcp_f32_e32 v83, v0
	v_mul_f32_e32 v0, 0xbfb8aa3b, v76
	v_exp_f32_e32 v0, v0
	v_pk_mul_f32 v[74:75], v[82:83], v[74:75]
	v_add_f32_e32 v0, 1.0, v0
	v_rcp_f32_e32 v82, v0
	v_mul_f32_e32 v0, 0xbfb8aa3b, v77
	v_exp_f32_e32 v0, v0
	s_nop 0
	v_add_f32_e32 v0, 1.0, v0
	v_rcp_f32_e32 v83, v0
	s_nop 0
	v_pk_mul_f32 v[76:77], v[82:83], v[76:77]
	v_pk_mul_f32 v[82:83], v[20:21], v[56:57] op_sel_hi:[1,0]
	v_lshlrev_b32_e32 v20, 16, v86
	v_mul_f32_e32 v0, 0xbfb8aa3b, v20
	v_exp_f32_e32 v0, v0
	v_and_b32_e32 v21, 0xffff0000, v86
	v_pk_mul_f32 v[98:99], v[82:83], v[82:83]
	v_add_f32_e32 v0, 1.0, v0
	v_rcp_f32_e32 v84, v0
	v_mul_f32_e32 v0, 0xbfb8aa3b, v21
	v_exp_f32_e32 v0, v0
	s_nop 0
	v_add_f32_e32 v0, 1.0, v0
	v_rcp_f32_e32 v85, v0
	s_nop 0
	v_pk_mul_f32 v[84:85], v[84:85], v[20:21]
	v_lshlrev_b32_e32 v20, 16, v87
	v_mul_f32_e32 v0, 0xbfb8aa3b, v20
	v_exp_f32_e32 v0, v0
	v_and_b32_e32 v21, 0xffff0000, v87
	v_add_f32_e32 v0, 1.0, v0
	v_rcp_f32_e32 v86, v0
	v_mul_f32_e32 v0, 0xbfb8aa3b, v21
	v_exp_f32_e32 v0, v0
	s_nop 0
	v_add_f32_e32 v0, 1.0, v0
	v_rcp_f32_e32 v87, v0
	v_add_f32_e32 v0, v64, v65
	v_add_f32_e32 v0, v62, v0
	v_add_f32_e32 v0, v63, v0
	v_add_f32_e32 v0, v72, v0
	v_add_f32_e32 v0, v73, v0
	v_add_f32_e32 v0, v70, v0
	v_add_f32_e32 v0, v71, v0
	v_add_f32_e32 v0, v80, v0
	v_add_f32_e32 v0, v81, v0
	v_add_f32_e32 v0, v78, v0
	v_add_f32_e32 v0, v79, v0
	v_add_f32_e32 v0, v90, v0
	v_add_f32_e32 v0, v91, v0
	v_add_f32_e32 v0, v88, v0
	v_add_f32_e32 v0, v89, v0
	v_add_f32_e32 v0, v94, v0
	v_add_f32_e32 v0, v95, v0
	v_add_f32_e32 v0, v92, v0
	v_add_f32_e32 v0, v93, v0
	v_add_f32_e32 v0, v98, v0
	v_add_f32_e32 v0, v99, v0
	v_add_f32_e32 v0, v96, v0
	v_add_f32_e32 v0, v97, v0
	v_add_f32_e32 v0, v100, v0
	v_add_f32_e32 v0, v101, v0
	v_add_f32_e32 v0, v26, v0
	v_add_f32_e32 v0, v27, v0
	v_add_f32_e32 v0, v28, v0
	v_add_f32_e32 v0, v29, v0
	v_add_f32_e32 v0, v30, v0
	v_add_f32_e32 v0, v31, v0
	ds_bpermute_b32 v26, v114, v0
	v_pk_mul_f32 v[86:87], v[86:87], v[20:21]
	v_mov_b64_e32 v[20:21], v[250:251]
	s_waitcnt lgkmcnt(0)
	v_add_f32_e32 v0, v0, v26
	v_fmamk_f32 v0, v0, 0x3c800000, v211
	v_cmp_gt_f32_e32 vcc, s55, v0
	v_mul_f32_e32 v26, 0x4f800000, v0
	s_nop 0
	v_cndmask_b32_e32 v0, v0, v26, vcc
	v_sqrt_f32_e32 v26, v0
	s_nop 0
	v_add_u32_e32 v27, -1, v26
	v_fma_f32 v28, -v27, v26, v0
	v_cmp_ge_f32_e64 s[0:1], 0, v28
	v_add_u32_e32 v28, 1, v26
	s_nop 0
	v_cndmask_b32_e64 v27, v26, v27, s[0:1]
	v_fma_f32 v26, -v28, v26, v0
	v_cmp_lt_f32_e64 s[0:1], 0, v26
	s_nop 1
	v_cndmask_b32_e64 v26, v27, v28, s[0:1]
	v_mul_f32_e32 v27, 0x37800000, v26
	v_cndmask_b32_e32 v26, v26, v27, vcc
	v_cmp_class_f32_e32 vcc, v0, v212
	s_nop 1
	v_cndmask_b32_e32 v0, v26, v0, vcc
	v_div_scale_f32 v26, s[0:1], v0, v0, 1.0
	v_rcp_f32_e32 v27, v26
	s_mov_b64 s[0:1], 0
	v_fma_f32 v28, -v26, v27, 1.0
	v_fmac_f32_e32 v27, v28, v27
	v_div_scale_f32 v28, vcc, 1.0, v0, 1.0
	v_mul_f32_e32 v29, v28, v27
	v_fma_f32 v30, -v26, v29, v28
	v_fmac_f32_e32 v29, v30, v27
	v_fma_f32 v26, -v26, v29, v28
	v_div_fmas_f32 v26, v26, v27, v29
	v_div_fixup_f32 v0, v26, v0, 1.0
	v_pk_mul_f32 v[26:27], v[32:33], v[0:1] op_sel_hi:[1,0]
	v_pk_mul_f32 v[16:17], v[16:17], v[0:1] op_sel_hi:[1,0]
	v_pk_mul_f32 v[2:3], v[2:3], v[26:27]
	v_pk_mul_f32 v[26:27], v[34:35], v[0:1] op_sel_hi:[1,0]
	v_pk_mul_f32 v[2:3], v[48:49], v[2:3]
	v_pk_mul_f32 v[4:5], v[4:5], v[26:27]
	v_cvt_pk_bf16_f32 v2, v2, v3
	v_pk_mul_f32 v[4:5], v[50:51], v[4:5]
	v_pk_mul_f32 v[26:27], v[36:37], v[0:1] op_sel_hi:[1,0]
	v_cvt_pk_bf16_f32 v3, v4, v5
	global_store_dwordx2 v[10:11], v[2:3], off
	global_load_dwordx4 v[2:5], v57, s[2:3] offset:32
	v_pk_mul_f32 v[14:15], v[14:15], v[0:1] op_sel_hi:[1,0]
	v_pk_mul_f32 v[8:9], v[8:9], v[0:1] op_sel_hi:[1,0]
	v_pk_mul_f32 v[6:7], v[6:7], v[0:1] op_sel_hi:[1,0]
	s_waitcnt vmcnt(0)
; __device__ __forceinline__ unsigned pk2(float lo, float hi) { f32x2 v = {lo, hi}; bf16x2_t b = __builtin_convertvector(v, bf16x2_t); return __builtin_bit_cast(unsigned, b); }
; __device__ __forceinline__ float bflo(unsigned u) { return __uint_as_float(u << 16); }
; __device__ __forceinline__ float bfhi(unsigned u) { return __uint_as_float(u & 0xffff0000u); }
; __device__ __forceinline__ float silu(float g) { return g * __builtin_amdgcn_rcpf(1.0f + __expf(-g)); }
; template <int MODE>
; __device__ __forceinline__ void attn_item(const AttnP& p, int b, int h, int qb, LAS unsigned char* lds) {
;     ...
; #pragma unroll
;     for (int d = 0; d < DV / 32; ++d)
; #pragma unroll
;         for (int g = 0; g < 4; ++g) {
;             const int dd = d * 32 + 8 * g + 4 * hh;
;             const u32x2 gr = *(const u32x2*)(P + trow * PP + gcol + dd);
;             const f32x4 og = *(const f32x4*)(p.out_gain + gaincol + dd);
;             const float o0 = O[0][d][4 * g] * rn * og[0] * silu(bflo(gr.x)), o1 = O[0][d][4 * g + 1] * rn * og[1] * silu(bfhi(gr.x));
;             const float o2 = O[0][d][4 * g + 2] * rn * og[2] * silu(bflo(gr.y)), o3 = O[0][d][4 * g + 3] * rn * og[3] * silu(bfhi(gr.y));
;             u32x2 wv; wv.x = pk2(o0, o1); wv.y = pk2(o2, o3);
;             *(u32x2*)(p.mixed + trow * 1024 + mixcol + dd) = wv;
;         }
	v_pk_mul_f32 v[2:3], v[2:3], v[26:27]
	v_pk_mul_f32 v[26:27], v[38:39], v[0:1] op_sel_hi:[1,0]
	v_pk_mul_f32 v[2:3], v[52:53], v[2:3]
	v_pk_mul_f32 v[4:5], v[4:5], v[26:27]
	v_cvt_pk_bf16_f32 v2, v2, v3
	v_pk_mul_f32 v[4:5], v[54:55], v[4:5]
	v_pk_mul_f32 v[26:27], v[58:59], v[0:1] op_sel_hi:[1,0]
	v_cvt_pk_bf16_f32 v3, v4, v5
	global_store_dwordx2 v[10:11], v[2:3], off offset:16
	global_load_dwordx4 v[2:5], v57, s[2:3] offset:64
	s_waitcnt vmcnt(0)
	v_pk_mul_f32 v[2:3], v[2:3], v[26:27]
	v_pk_mul_f32 v[26:27], v[42:43], v[0:1] op_sel_hi:[1,0]
	v_pk_mul_f32 v[2:3], v[60:61], v[2:3]
	v_pk_mul_f32 v[4:5], v[4:5], v[26:27]
	v_cvt_pk_bf16_f32 v2, v2, v3
	v_pk_mul_f32 v[4:5], v[40:41], v[4:5]
	v_pk_mul_f32 v[26:27], v[66:67], v[0:1] op_sel_hi:[1,0]
	v_cvt_pk_bf16_f32 v3, v4, v5
	global_store_dwordx2 v[10:11], v[2:3], off offset:32
	global_load_dwordx4 v[2:5], v57, s[2:3] offset:96
	s_waitcnt vmcnt(0)
	v_pk_mul_f32 v[2:3], v[2:3], v[26:27]
	v_pk_mul_f32 v[26:27], v[46:47], v[0:1] op_sel_hi:[1,0]
	v_pk_mul_f32 v[2:3], v[68:69], v[2:3]
	v_pk_mul_f32 v[4:5], v[4:5], v[26:27]
	v_cvt_pk_bf16_f32 v2, v2, v3
	v_pk_mul_f32 v[4:5], v[44:45], v[4:5]
	s_nop 0
	v_cvt_pk_bf16_f32 v3, v4, v5
	global_store_dwordx2 v[10:11], v[2:3], off offset:48
	global_load_dwordx4 v[2:5], v57, s[2:3] offset:128
	s_waitcnt vmcnt(0)
	v_pk_mul_f32 v[2:3], v[2:3], v[16:17]
	v_pk_mul_f32 v[16:17], v[18:19], v[0:1] op_sel_hi:[1,0]
	v_pk_mul_f32 v[2:3], v[74:75], v[2:3]
	v_pk_mul_f32 v[4:5], v[4:5], v[16:17]
	v_cvt_pk_bf16_f32 v2, v2, v3
	v_pk_mul_f32 v[4:5], v[76:77], v[4:5]
	v_pk_mul_f32 v[16:17], v[82:83], v[0:1] op_sel_hi:[1,0]
	v_cvt_pk_bf16_f32 v3, v4, v5
	global_store_dwordx2 v[10:11], v[2:3], off offset:64
	global_load_dwordx4 v[2:5], v57, s[2:3] offset:160
	s_waitcnt vmcnt(0)
	v_pk_mul_f32 v[2:3], v[2:3], v[16:17]
	v_pk_mul_f32 v[16:17], v[22:23], v[0:1] op_sel_hi:[1,0]
	v_pk_mul_f32 v[2:3], v[84:85], v[2:3]
	v_pk_mul_f32 v[4:5], v[4:5], v[16:17]
	v_cvt_pk_bf16_f32 v2, v2, v3
	v_pk_mul_f32 v[4:5], v[86:87], v[4:5]
	v_lshlrev_b32_e32 v16, 16, v20
	v_cvt_pk_bf16_f32 v3, v4, v5
	global_store_dwordx2 v[10:11], v[2:3], off offset:80
	global_load_dwordx4 v[2:5], v57, s[2:3] offset:192
	v_and_b32_e32 v17, 0xffff0000, v20
	v_mul_f32_e32 v18, 0xbfb8aa3b, v16
	v_mul_f32_e32 v19, 0xbfb8aa3b, v17
	v_exp_f32_e32 v18, v18
	v_exp_f32_e32 v19, v19
	v_pk_mul_f32 v[22:23], v[24:25], v[0:1] op_sel_hi:[1,0]
	v_add_f32_e32 v18, 1.0, v18
	v_add_f32_e32 v19, 1.0, v19
	v_rcp_f32_e32 v18, v18
	v_rcp_f32_e32 v19, v19
	s_waitcnt vmcnt(0)
	v_pk_mul_f32 v[2:3], v[2:3], v[22:23]
	v_pk_mul_f32 v[16:17], v[18:19], v[16:17]
	v_pk_mul_f32 v[4:5], v[4:5], v[14:15]
	v_pk_mul_f32 v[2:3], v[16:17], v[2:3]
	v_lshlrev_b32_e32 v16, 16, v21
	v_and_b32_e32 v17, 0xffff0000, v21
	v_mul_f32_e32 v18, 0xbfb8aa3b, v16
	v_mul_f32_e32 v14, 0xbfb8aa3b, v17
	v_exp_f32_e32 v18, v18
	v_exp_f32_e32 v14, v14
	v_cvt_pk_bf16_f32 v2, v2, v3
	v_add_f32_e32 v18, 1.0, v18
	v_add_f32_e32 v14, 1.0, v14
	v_rcp_f32_e32 v18, v18
	v_rcp_f32_e32 v19, v14
	s_nop 0
	v_pk_mul_f32 v[14:15], v[18:19], v[16:17]
	s_nop 0
	v_pk_mul_f32 v[4:5], v[14:15], v[4:5]
	s_nop 0
	v_cvt_pk_bf16_f32 v3, v4, v5
	global_store_dwordx2 v[10:11], v[2:3], off offset:96
	v_mov_b64_e32 v[2:3], v[248:249]
	s_nop 0
	global_load_dwordx4 v[12:15], v57, s[2:3] offset:224
	v_readlane_b32 s3, v252, 9
	s_waitcnt vmcnt(0) lgkmcnt(0)
	v_lshlrev_b32_e32 v4, 16, v2
	v_and_b32_e32 v5, 0xffff0000, v2
	v_mul_f32_e32 v2, 0xbfb8aa3b, v4
	v_exp_f32_e32 v2, v2
	v_pk_mul_f32 v[8:9], v[12:13], v[8:9]
	v_pk_mul_f32 v[6:7], v[14:15], v[6:7]
	v_add_f32_e32 v2, 1.0, v2
	v_rcp_f32_e32 v16, v2
	v_mul_f32_e32 v2, 0xbfb8aa3b, v5
	v_exp_f32_e32 v2, v2
	s_nop 0
	v_add_f32_e32 v2, 1.0, v2
	v_rcp_f32_e32 v17, v2
	v_lshlrev_b32_e32 v2, 16, v3
	v_and_b32_e32 v3, 0xffff0000, v3
	v_mul_f32_e32 v0, 0xbfb8aa3b, v3
	v_pk_mul_f32 v[4:5], v[16:17], v[4:5]
	v_exp_f32_e32 v0, v0
	v_pk_mul_f32 v[4:5], v[4:5], v[8:9]
	v_mul_f32_e32 v8, 0xbfb8aa3b, v2
	v_exp_f32_e32 v8, v8
	v_add_f32_e32 v0, 1.0, v0
	v_rcp_f32_e32 v9, v0
	v_cvt_pk_bf16_f32 v4, v4, v5
	v_add_f32_e32 v8, 1.0, v8
	v_rcp_f32_e32 v8, v8
	s_nop 0
	v_pk_mul_f32 v[2:3], v[8:9], v[2:3]
	s_nop 0
	v_pk_mul_f32 v[2:3], v[2:3], v[6:7]
	s_nop 0
	v_cvt_pk_bf16_f32 v5, v2, v3
	global_store_dwordx2 v[10:11], v[4:5], off offset:112
	v_mov_b64_e32 v[194:195], 0x880
	v_mov_b64_e32 v[196:197], 0x87f
	v_mov_b64_e32 v[198:199], 0x800
	v_mov_b64_e32 v[200:201], 0x7ff
	v_mov_b64_e32 v[202:203], 0x200
	v_mov_b64_e32 v[204:205], 0x1ff
